# LayerNorm phase: prefetched row loads no longer waited right after issue (bf16 unpack moved to loop end behind counted vmcnt(8), in-loop y waits relaxed by the 16 younger loads), on top of v19
# speedup vs baseline: 1.0058x; 1.0027x over previous
; __device__ __forceinline__ void ln_phase(const Params& p, int layer, float* hf, bf16_t* hb, const bf16_t* yb, const float* g, const float* b, int blk, int G, int tid) {
;     const int lane = tid & 63, wave = tid >> 6;
;     f32x4 v[8]; u32x2 y[8];
;     ...
;     f32x4 gam[8], bet[8];
; #pragma unroll
;     for (int j = 0; j < 8; ++j) { gam[j] = *(const f32x4*)(g + j * 256 + lane * 4); bet[j] = *(const f32x4*)(b + j * 256 + lane * 4); }
;     int m = blk * 8 + wave;
;     f32x4 v2[8]; u32x2 y2[8];
; #pragma unroll
;     for (int j = 0; j < 8; ++j) { v2[j] = (f32x4){0.f, 0.f, 0.f, 0.f}; y2[j] = (u32x2){0u, 0u}; }
;     if (m < MT) LN_LOAD(v, y, m);
;     if (m + G * 8 < MT) LN_LOAD(v2, y2, m + G * 8);
.LBB0_568:
	s_or_b64 exec, exec, s[2:3]
	s_and_saveexec_b64 s[2:3], s[4:5]
	s_cbranch_execz .LBB0_581
	v_readlane_b32 s6, v253, 24
	v_lshlrev_b32_e32 v0, 1, v180
	v_readlane_b32 s7, v253, 25
	v_lshl_add_u64 v[178:179], s[84:85], 0, v[0:1]
	v_xor_b32_e32 v131, 1, v213
	v_lshl_add_u64 v[180:181], s[6:7], 0, v[0:1]
	v_and_b32_e32 v0, 64, v213
	v_add_u32_e32 v0, 64, v0
	v_cmp_lt_i32_e32 vcc, v131, v0
	v_readlane_b32 s4, v255, 24
	v_readlane_b32 s5, v255, 25
	v_cndmask_b32_e32 v131, v213, v131, vcc
	v_lshlrev_b32_e32 v133, 2, v131
	v_xor_b32_e32 v131, 2, v213
	v_cmp_lt_i32_e32 vcc, v131, v0
	s_mov_b32 s12, s4
	s_cmp_lg_u32 s4, 0
	v_cndmask_b32_e32 v131, v213, v131, vcc
	v_lshlrev_b32_e32 v215, 2, v131
	v_xor_b32_e32 v131, 4, v213
	v_cmp_lt_i32_e32 vcc, v131, v0
	s_cselect_b64 s[4:5], -1, 0
	s_cmp_lg_u32 s12, 3
	v_cndmask_b32_e32 v131, v213, v131, vcc
	v_lshlrev_b32_e32 v216, 2, v131
	v_xor_b32_e32 v131, 8, v213
	v_cmp_lt_i32_e32 vcc, v131, v0
	s_cselect_b64 s[6:7], -1, 0
	v_ashrrev_i32_e32 v183, 31, v182
	v_cndmask_b32_e32 v131, v213, v131, vcc
	v_lshlrev_b32_e32 v217, 2, v131
	v_xor_b32_e32 v131, 16, v213
	v_cmp_lt_i32_e32 vcc, v131, v0
	s_ashr_i32 s9, s8, 31
	v_lshl_add_u64 v[152:153], v[182:183], 0, s[8:9]
	v_cndmask_b32_e32 v131, v213, v131, vcc
	v_lshlrev_b32_e32 v218, 2, v131
	v_xor_b32_e32 v131, 32, v213
	v_cmp_lt_i32_e32 vcc, v131, v0
	v_lshlrev_b64 v[182:183], 13, v[152:153]
	v_readlane_b32 s8, v254, 63
	v_cndmask_b32_e32 v0, v213, v131, vcc
	v_lshlrev_b32_e32 v219, 2, v0
	v_and_b32_e32 v0, 63, v135
	v_lshl_or_b32 v182, v0, 4, v182
	v_readlane_b32 s9, v255, 0
	v_lshlrev_b64 v[152:153], 12, v[152:153]
	v_ashrrev_i32_e32 v135, 31, v134
	v_lshl_add_u64 v[182:183], s[8:9], 0, v[182:183]
	v_readlane_b32 s8, v255, 1
	v_lshl_or_b32 v152, v0, 3, v152
	v_readlane_b32 s9, v255, 2
	v_lshlrev_b64 v[184:185], 13, v[134:135]
	s_lshl_b32 s14, s10, 4
	v_lshl_add_u64 v[186:187], s[8:9], 0, v[152:153]
	v_lshlrev_b64 v[188:189], 12, v[134:135]
	s_mov_b64 s[8:9], 0
	s_waitcnt vmcnt(0)
	s_branch .LBB0_571
.LBB0_570:
	s_waitcnt vmcnt(8)
	s_and_b64 vcc, exec, s[4:5]
	s_cbranch_vccz .Lln_skip_unpk
	v_lshlrev_b32_e32 v90, 16, v92
	v_and_b32_e32 v91, 0xffff0000, v92
	v_lshlrev_b32_e32 v92, 16, v93
	v_and_b32_e32 v93, 0xffff0000, v93
	v_lshlrev_b32_e32 v94, 16, v96
	v_and_b32_e32 v95, 0xffff0000, v96
	v_lshlrev_b32_e32 v96, 16, v97
	v_and_b32_e32 v97, 0xffff0000, v97
	v_lshlrev_b32_e32 v106, 16, v108
	v_and_b32_e32 v107, 0xffff0000, v108
	v_lshlrev_b32_e32 v108, 16, v109
	v_and_b32_e32 v109, 0xffff0000, v109
	v_lshlrev_b32_e32 v110, 16, v112
	v_and_b32_e32 v111, 0xffff0000, v112
	v_lshlrev_b32_e32 v112, 16, v113
	v_and_b32_e32 v113, 0xffff0000, v113
	v_lshlrev_b32_e32 v114, 16, v116
	v_and_b32_e32 v115, 0xffff0000, v116
	v_lshlrev_b32_e32 v116, 16, v117
	v_and_b32_e32 v117, 0xffff0000, v117
	v_lshlrev_b32_e32 v118, 16, v120
	v_and_b32_e32 v119, 0xffff0000, v120
	v_lshlrev_b32_e32 v120, 16, v121
	v_and_b32_e32 v121, 0xffff0000, v121
	v_lshlrev_b32_e32 v122, 16, v124
	v_and_b32_e32 v123, 0xffff0000, v124
	v_lshlrev_b32_e32 v124, 16, v125
	v_and_b32_e32 v125, 0xffff0000, v125
	v_lshlrev_b32_e32 v126, 16, v128
	v_and_b32_e32 v127, 0xffff0000, v128
	v_lshlrev_b32_e32 v128, 16, v129
	v_and_b32_e32 v129, 0xffff0000, v129

; __device__ __forceinline__ void ln_phase(const Params& p, int layer, float* hf, bf16_t* hb, const bf16_t* yb, const float* g, const float* b, int blk, int G, int tid) {
;     ...
;     while (m < MT) {
;         const int mn = m + G * 8, mn2 = m + 2 * G * 8;
;         f32x4 v3[8]; u32x2 y3[8];
; #pragma unroll
;         for (int j = 0; j < 8; ++j) { v3[j] = (f32x4){0.f, 0.f, 0.f, 0.f}; y3[j] = (u32x2){0u, 0u}; }
;         if (mn2 < MT) LN_LOAD(v3, y3, mn2);
;     ...
;         for (int j = 0; j < 8; ++j) { v[j] = v2[j]; y[j] = y2[j]; v2[j] = v3[j]; y2[j] = y3[j]; }
.LBB0_571:
	v_add_u32_e32 v206, s14, v132
	s_mov_b32 s10, 0x8200
	v_mov_b32_e32 v0, v1
	s_waitcnt vmcnt(15)
	v_mov_b32_e32 v226, v93
	v_mov_b32_e32 v234, v92
	v_mov_b32_e32 v242, v91
	v_mov_b32_e32 v250, v90
	s_waitcnt vmcnt(14)
	v_mov_b32_e32 v225, v97
	v_mov_b32_e32 v233, v96
	v_mov_b32_e32 v241, v95
	v_mov_b32_e32 v249, v94
	s_waitcnt vmcnt(13)
	v_mov_b32_e32 v224, v109
	v_mov_b32_e32 v232, v108
	v_mov_b32_e32 v240, v107
	v_mov_b32_e32 v248, v106
	s_waitcnt vmcnt(12)
	v_mov_b32_e32 v223, v113
	v_mov_b32_e32 v231, v112
	v_mov_b32_e32 v239, v111
	v_mov_b32_e32 v247, v110
	s_waitcnt vmcnt(11)
	v_mov_b32_e32 v222, v117
	v_mov_b32_e32 v230, v116
	v_mov_b32_e32 v238, v115
	v_mov_b32_e32 v246, v114
	s_waitcnt vmcnt(10)
	v_mov_b32_e32 v221, v121
	v_mov_b32_e32 v229, v120
	v_mov_b32_e32 v237, v119
	v_mov_b32_e32 v245, v118
	s_waitcnt vmcnt(9)
	v_mov_b32_e32 v220, v125
	v_mov_b32_e32 v228, v124
	v_mov_b32_e32 v236, v123
	v_mov_b32_e32 v244, v122
	s_waitcnt vmcnt(8)
	v_mov_b32_e32 v135, v129
	v_mov_b32_e32 v227, v128
	v_mov_b32_e32 v235, v127
	v_mov_b32_e32 v243, v126
	v_cmp_gt_i32_e32 vcc, s10, v206
	v_mov_b32_e32 v93, 0
	v_mov_b32_e32 v92, 0
	v_mov_b32_e32 v91, 0
	v_mov_b32_e32 v90, 0
	v_mov_b32_e32 v97, 0
	v_mov_b32_e32 v96, 0
	v_mov_b32_e32 v95, 0
	v_mov_b32_e32 v94, 0
	v_mov_b32_e32 v109, 0
	v_mov_b32_e32 v108, 0
	v_mov_b32_e32 v107, 0
	v_mov_b32_e32 v106, 0
	v_mov_b32_e32 v113, 0
	v_mov_b32_e32 v112, 0
	v_mov_b32_e32 v111, 0
	v_mov_b32_e32 v110, 0
	v_mov_b32_e32 v117, 0
	v_mov_b32_e32 v116, 0
	v_mov_b32_e32 v115, 0
	v_mov_b32_e32 v114, 0
	v_mov_b32_e32 v121, 0
	v_mov_b32_e32 v120, 0
	v_mov_b32_e32 v119, 0
	v_mov_b32_e32 v118, 0
	v_mov_b32_e32 v125, 0
	v_mov_b32_e32 v124, 0
	v_mov_b32_e32 v123, 0
	v_mov_b32_e32 v122, 0
	v_mov_b32_e32 v129, 0
	v_mov_b32_e32 v128, 0
	v_mov_b32_e32 v127, 0
	v_mov_b32_e32 v126, 0
	v_mov_b64_e32 v[190:191], v[0:1]
	v_mov_b64_e32 v[192:193], v[0:1]
	v_mov_b64_e32 v[194:195], v[0:1]
	v_mov_b64_e32 v[196:197], v[0:1]
	v_mov_b64_e32 v[198:199], v[0:1]
	v_mov_b64_e32 v[200:201], v[0:1]
	v_mov_b64_e32 v[202:203], v[0:1]
	v_mov_b64_e32 v[204:205], v[0:1]
	s_and_saveexec_b64 s[10:11], vcc
	s_cbranch_execz .LBB0_576
	v_ashrrev_i32_e32 v207, 31, v206
	v_lshlrev_b64 v[190:191], 11, v[206:207]
	s_and_b64 vcc, exec, s[4:5]
	s_cbranch_vccz .LBB0_580
	v_lshl_add_u64 v[90:91], v[190:191], 1, v[180:181]
	global_load_dwordx2 v[92:93], v[90:91], off nt
	global_load_dwordx2 v[96:97], v[90:91], off offset:512 nt
	global_load_dwordx2 v[108:109], v[90:91], off offset:1024 nt
	global_load_dwordx2 v[112:113], v[90:91], off offset:1536 nt
	global_load_dwordx2 v[116:117], v[90:91], off offset:2048 nt
	global_load_dwordx2 v[120:121], v[90:91], off offset:2560 nt
	global_load_dwordx2 v[124:125], v[90:91], off offset:3072 nt
	global_load_dwordx2 v[128:129], v[90:91], off offset:3584 nt
	s_cbranch_execnz .LBB0_575

; #define UNPK4(D, W) do { D[0] = __uint_as_float((W)[0] << 16); D[1] = __uint_as_float((W)[0] & 0xffff0000u); D[2] = __uint_as_float((W)[1] << 16); D[3] = __uint_as_float((W)[1] & 0xffff0000u); } while (0)
; __device__ __forceinline__ void ln_phase(const Params& p, int layer, float* hf, bf16_t* hb, const bf16_t* yb, const float* g, const float* b, int blk, int G, int tid) {
;     ...
;         float s = 0.f;
; #pragma unroll
;         for (int j = 0; j < 8; ++j) { f32x4 yy; UNPK4(yy, y[j]); v[j] = v[j] * ALPHA_RES + yy; s += (v[j][0] + v[j][1]) + (v[j][2] + v[j][3]); }
;         const float mean = wave_sum(s) * (1.f / DM); float s2 = 0.f;
.LBB0_576:
	s_or_b64 exec, exec, s[10:11]
	s_waitcnt vmcnt(23)
	v_lshlrev_b32_e32 v152, 16, v176
	v_and_b32_e32 v153, 0xffff0000, v176
	s_mov_b32 s10, 0x3fd744fd
	v_pk_fma_f32 v[102:103], v[102:103], s[10:11], v[152:153] op_sel_hi:[1,0,1]
	s_waitcnt vmcnt(22)
	v_lshlrev_b32_e32 v152, 16, v174
	v_and_b32_e32 v153, 0xffff0000, v174
	v_lshlrev_b32_e32 v176, 16, v177
	v_and_b32_e32 v177, 0xffff0000, v177
	v_lshlrev_b32_e32 v174, 16, v175
	v_and_b32_e32 v175, 0xffff0000, v175
	v_pk_fma_f32 v[98:99], v[98:99], s[10:11], v[152:153] op_sel_hi:[1,0,1]
	v_pk_fma_f32 v[104:105], v[104:105], s[10:11], v[176:177] op_sel_hi:[1,0,1]
	v_pk_fma_f32 v[100:101], v[100:101], s[10:11], v[174:175] op_sel_hi:[1,0,1]
	v_mov_b32_e32 v152, v98
	v_mov_b32_e32 v153, v102
	v_mov_b32_e32 v174, v99
	v_mov_b32_e32 v175, v103
	v_pk_add_f32 v[152:153], v[152:153], v[174:175]
	v_mov_b32_e32 v174, v100
	v_mov_b32_e32 v175, v104
	v_mov_b32_e32 v176, v101
	v_mov_b32_e32 v177, v105
	v_pk_add_f32 v[174:175], v[174:175], v[176:177]
	s_waitcnt vmcnt(19)
	v_lshlrev_b32_e32 v176, 16, v142
	v_pk_add_f32 v[152:153], v[152:153], v[174:175]
	v_lshlrev_b32_e32 v174, 16, v172
	v_and_b32_e32 v175, 0xffff0000, v172
	v_lshlrev_b32_e32 v172, 16, v173
	v_and_b32_e32 v173, 0xffff0000, v173
	v_pk_fma_f32 v[88:89], v[88:89], s[10:11], v[172:173] op_sel_hi:[1,0,1]
	v_pk_fma_f32 v[86:87], v[86:87], s[10:11], v[174:175] op_sel_hi:[1,0,1]
	v_mov_b32_e32 v175, v89
	v_pk_mov_b32 v[172:173], v[86:87], v[88:89] op_sel:[1,0]
	v_mov_b32_e32 v174, v86
	v_pk_add_f32 v[172:173], v[172:173], v[174:175]
	v_lshlrev_b32_e32 v174, 16, v170
	v_and_b32_e32 v175, 0xffff0000, v170
	v_lshlrev_b32_e32 v170, 16, v171
	v_and_b32_e32 v171, 0xffff0000, v171
	v_and_b32_e32 v177, 0xffff0000, v142
	v_lshlrev_b32_e32 v142, 16, v143
	v_and_b32_e32 v143, 0xffff0000, v143
	v_add_f32_e32 v0, 0, v153
	v_pk_add_f32 v[172:173], v[172:173], v[172:173] op_sel_hi:[0,1]
	v_pk_fma_f32 v[84:85], v[84:85], s[10:11], v[170:171] op_sel_hi:[1,0,1]
	v_pk_fma_f32 v[82:83], v[82:83], s[10:11], v[174:175] op_sel_hi:[1,0,1]
	v_pk_fma_f32 v[80:81], v[80:81], s[10:11], v[142:143] op_sel_hi:[1,0,1]
	v_pk_fma_f32 v[78:79], v[78:79], s[10:11], v[176:177] op_sel_hi:[1,0,1]
	v_add_f32_e32 v153, v152, v0
	v_add_f32_e32 v171, v82, v83
	v_add_f32_e32 v175, v84, v85
	v_mov_b32_e32 v170, v78
	v_mov_b32_e32 v174, v79
	v_mov_b32_e32 v172, v80
	v_mov_b32_e32 v152, v81
	v_pk_add_f32 v[142:143], v[170:171], v[174:175]
	v_pk_add_f32 v[152:153], v[172:173], v[152:153]
	s_waitcnt vmcnt(16)
	v_lshlrev_b32_e32 v172, 16, v136
	v_pk_add_f32 v[142:143], v[142:143], v[152:153]
	v_lshlrev_b32_e32 v152, 16, v140
	v_and_b32_e32 v153, 0xffff0000, v140
	v_lshlrev_b32_e32 v140, 16, v141
	v_and_b32_e32 v141, 0xffff0000, v141
	v_pk_fma_f32 v[76:77], v[76:77], s[10:11], v[140:141] op_sel_hi:[1,0,1]
	v_pk_fma_f32 v[140:141], v[74:75], s[10:11], v[152:153] op_sel_hi:[1,0,1]
	v_mov_b32_e32 v153, v77
	v_pk_mov_b32 v[74:75], v[140:141], v[76:77] op_sel:[1,0]
	v_mov_b32_e32 v152, v140
	v_pk_add_f32 v[74:75], v[74:75], v[152:153]
	v_lshlrev_b32_e32 v152, 16, v138
	v_and_b32_e32 v153, 0xffff0000, v138
	v_lshlrev_b32_e32 v138, 16, v139
	v_and_b32_e32 v139, 0xffff0000, v139
	v_pk_fma_f32 v[152:153], v[70:71], s[10:11], v[152:153] op_sel_hi:[1,0,1]
	v_and_b32_e32 v173, 0xffff0000, v136
	v_lshlrev_b32_e32 v70, 16, v137
	v_and_b32_e32 v71, 0xffff0000, v137
	v_pk_add_f32 v[142:143], v[142:143], v[142:143] op_sel_hi:[0,1]
	v_pk_add_f32 v[74:75], v[74:75], v[74:75] op_sel_hi:[0,1]
	v_pk_fma_f32 v[72:73], v[72:73], s[10:11], v[138:139] op_sel_hi:[1,0,1]
	v_pk_fma_f32 v[70:71], v[68:69], s[10:11], v[70:71] op_sel_hi:[1,0,1]
	v_pk_fma_f32 v[172:173], v[66:67], s[10:11], v[172:173] op_sel_hi:[1,0,1]
	v_add_f32_e32 v139, v152, v153
	v_add_f32_e32 v171, v72, v73
	v_mov_b32_e32 v138, v172
	v_mov_b32_e32 v170, v173
	v_mov_b32_e32 v74, v70
	v_mov_b32_e32 v142, v71
	v_pk_add_f32 v[66:67], v[138:139], v[170:171]
	v_pk_add_f32 v[68:69], v[74:75], v[142:143]
	s_mov_b32 s10, 0x800000
	v_pk_add_f32 v[66:67], v[66:67], v[68:69]
	s_nop 0
	v_add_f32_e32 v0, v66, v67
	ds_bpermute_b32 v66, v133, v0
	s_waitcnt lgkmcnt(0)
	v_add_f32_e32 v0, v0, v66
	ds_bpermute_b32 v66, v215, v0
	s_waitcnt lgkmcnt(0)
	v_add_f32_e32 v0, v0, v66
	ds_bpermute_b32 v66, v216, v0
	s_waitcnt lgkmcnt(0)
	v_add_f32_e32 v0, v0, v66
	ds_bpermute_b32 v66, v217, v0
	s_waitcnt lgkmcnt(0)
	v_add_f32_e32 v0, v0, v66
	ds_bpermute_b32 v66, v218, v0
	s_waitcnt lgkmcnt(0)
	v_add_f32_e32 v0, v0, v66
	ds_bpermute_b32 v66, v219, v0
	s_waitcnt lgkmcnt(0)
; __device__ __forceinline__ u32x2 pack4(f32x4 a) { u32x2 w = {pk2(a[0], a[1]), pk2(a[2], a[3])}; return w; }
; __device__ __forceinline__ void ln_phase(const Params& p, int layer, float* hf, bf16_t* hb, const bf16_t* yb, const float* g, const float* b, int blk, int G, int tid) {
;     ...
;         const float mean = wave_sum(s) * (1.f / DM); float s2 = 0.f;
; #pragma unroll
;         for (int j = 0; j < 8; ++j) { v[j] = v[j] - mean; s2 += (v[j][0] * v[j][0] + v[j][1] * v[j][1]) + (v[j][2] * v[j][2] + v[j][3] * v[j][3]); }
;         const float rstd = rsqrtf(wave_sum(s2) * (1.f / DM) + 1e-5f);
;         if (layer == 3) { float* row = hf + (size_t)m * DM + lane * 4;
; #pragma unroll
;             for (int j = 0; j < 8; ++j) { const f32x4 gg = gam[j], bb = bet[j]; __builtin_nontemporal_store(v[j] * rstd * gg + bb, (f32x4*)(row + j * 256)); } }
;         else { bf16_t* orow = hb + (size_t)m * DM + lane * 4;
; #pragma unroll
;             for (int j = 0; j < 8; ++j) { const f32x4 gg = gam[j], bb = bet[j]; *(u32x2*)(orow + j * 256) = pack4(v[j] * rstd * gg + bb); } }
	v_add_f32_e32 v131, v0, v66
	v_fmamk_f32 v103, v131, 0xba000000, v103
	v_fmamk_f32 v99, v131, 0xba000000, v99
	v_fmamk_f32 v105, v131, 0xba000000, v105
	v_fmac_f32_e32 v102, 0xba000000, v131
	v_fmac_f32_e32 v98, 0xba000000, v131
	v_mov_b32_e32 v68, v103
	v_mov_b32_e32 v69, v99
	v_fmac_f32_e32 v104, 0xba000000, v131
	v_fmamk_f32 v75, v131, 0xba000000, v101
	v_fmac_f32_e32 v100, 0xba000000, v131
	v_mov_b32_e32 v66, v102
	v_mov_b32_e32 v67, v98
	v_pk_mul_f32 v[68:69], v[68:69], v[68:69]
	v_mov_b32_e32 v74, v105
	v_pk_fma_f32 v[66:67], v[66:67], v[66:67], v[68:69]
	v_mov_b32_e32 v68, v104
	v_mov_b32_e32 v69, v100
	v_pk_mul_f32 v[136:137], v[74:75], v[74:75]
	v_fmamk_f32 v89, v131, 0xba000000, v89
	v_pk_fma_f32 v[68:69], v[68:69], v[68:69], v[136:137]
	v_fmac_f32_e32 v88, 0xba000000, v131
	v_fmamk_f32 v87, v131, 0xba000000, v87
	v_fmac_f32_e32 v86, 0xba000000, v131
	v_pk_add_f32 v[66:67], v[66:67], v[68:69]
	v_pk_mul_f32 v[68:69], v[88:89], v[88:89]
	v_pk_mul_f32 v[136:137], v[86:87], v[86:87]
	v_fmac_f32_e32 v82, 0xba000000, v131
	v_pk_mov_b32 v[138:139], v[136:137], v[68:69] op_sel:[1,0]
	v_mov_b32_e32 v137, v69
	v_fmac_f32_e32 v84, 0xba000000, v131
	v_fmamk_f32 v83, v131, 0xba000000, v83
	v_mul_f32_e32 v0, v82, v82
	v_pk_add_f32 v[68:69], v[138:139], v[136:137]
	v_fmamk_f32 v85, v131, 0xba000000, v85
	v_pk_fma_f32 v[136:137], v[82:83], v[82:83], v[0:1] op_sel_hi:[1,1,0]
	v_mul_f32_e32 v0, v84, v84
	v_pk_add_f32 v[66:67], v[66:67], v[66:67] op_sel_hi:[0,1]
	v_pk_add_f32 v[68:69], v[68:69], v[68:69] op_sel_hi:[0,1]
	v_pk_fma_f32 v[138:139], v[84:85], v[84:85], v[0:1] op_sel_hi:[1,1,0]
	v_fmamk_f32 v81, v131, 0xba000000, v81
	v_fmac_f32_e32 v80, 0xba000000, v131
	v_fmamk_f32 v79, v131, 0xba000000, v79
	v_fmac_f32_e32 v78, 0xba000000, v131
	v_mul_f32_e32 v136, v78, v78
	v_mul_f32_e32 v138, v79, v79
	v_mul_f32_e32 v68, v80, v80
	v_mul_f32_e32 v66, v81, v81
	v_pk_add_f32 v[136:137], v[136:137], v[138:139]
	v_pk_add_f32 v[66:67], v[68:69], v[66:67]
	v_fmamk_f32 v77, v131, 0xba000000, v77
	v_fmac_f32_e32 v76, 0xba000000, v131
	v_fmamk_f32 v141, v131, 0xba000000, v141
	v_fmac_f32_e32 v140, 0xba000000, v131
	v_pk_add_f32 v[66:67], v[136:137], v[66:67]
	v_pk_mul_f32 v[68:69], v[76:77], v[76:77]
	v_pk_mul_f32 v[136:137], v[140:141], v[140:141]
	v_fmac_f32_e32 v152, 0xba000000, v131
	v_pk_mov_b32 v[138:139], v[136:137], v[68:69] op_sel:[1,0]
	v_mov_b32_e32 v137, v69
	v_fmac_f32_e32 v72, 0xba000000, v131
	v_fmamk_f32 v153, v131, 0xba000000, v153
	v_mul_f32_e32 v0, v152, v152
	v_pk_add_f32 v[68:69], v[138:139], v[136:137]
	v_fmamk_f32 v73, v131, 0xba000000, v73
	v_pk_fma_f32 v[136:137], v[152:153], v[152:153], v[0:1] op_sel_hi:[1,1,0]
	v_mul_f32_e32 v0, v72, v72
	v_pk_add_f32 v[66:67], v[66:67], v[66:67] op_sel_hi:[0,1]
	v_pk_add_f32 v[68:69], v[68:69], v[68:69] op_sel_hi:[0,1]
	v_pk_fma_f32 v[138:139], v[72:73], v[72:73], v[0:1] op_sel_hi:[1,1,0]
	v_fmamk_f32 v71, v131, 0xba000000, v71
	v_fmac_f32_e32 v70, 0xba000000, v131
	v_fmamk_f32 v173, v131, 0xba000000, v173
	v_fmac_f32_e32 v172, 0xba000000, v131
	v_mul_f32_e32 v136, v172, v172
	v_mul_f32_e32 v138, v173, v173
	v_mul_f32_e32 v68, v70, v70
	v_mul_f32_e32 v66, v71, v71
	v_pk_add_f32 v[136:137], v[136:137], v[138:139]
	v_pk_add_f32 v[66:67], v[68:69], v[66:67]
	s_nop 0
	v_pk_add_f32 v[66:67], v[136:137], v[66:67]
	s_nop 0
	v_add_f32_e32 v0, v66, v67
	ds_bpermute_b32 v66, v133, v0
	s_waitcnt lgkmcnt(0)
	v_add_f32_e32 v0, v0, v66
	ds_bpermute_b32 v66, v215, v0
	s_waitcnt lgkmcnt(0)
	v_add_f32_e32 v0, v0, v66
	ds_bpermute_b32 v66, v216, v0
	s_waitcnt lgkmcnt(0)
	v_add_f32_e32 v0, v0, v66
	ds_bpermute_b32 v66, v217, v0
	s_waitcnt lgkmcnt(0)
	v_add_f32_e32 v0, v0, v66
	ds_bpermute_b32 v66, v218, v0
	s_waitcnt lgkmcnt(0)
	v_add_f32_e32 v0, v0, v66
	ds_bpermute_b32 v66, v219, v0
	s_waitcnt lgkmcnt(0)
	v_add_f32_e32 v0, v0, v66
	v_fmamk_f32 v0, v0, 0x3a000000, v208
	v_mul_f32_e32 v66, 0x4b800000, v0
	v_cmp_gt_f32_e32 vcc, s10, v0
	s_mov_b64 s[10:11], -1
	s_nop 0
	v_cndmask_b32_e32 v0, v0, v66, vcc
	v_rsq_f32_e32 v0, v0
	s_nop 0
	v_mul_f32_e32 v66, 0x45800000, v0
	v_cndmask_b32_e32 v136, v0, v66, vcc
	v_mov_b32_e32 v137, v136
	v_pk_mul_f32 v[66:67], v[102:103], v[136:137] op_sel_hi:[1,0]
	v_pk_mul_f32 v[68:69], v[104:105], v[136:137] op_sel_hi:[1,0]
	v_pk_fma_f32 v[66:67], v[2:3], v[66:67], v[10:11]
	v_pk_fma_f32 v[68:69], v[4:5], v[68:69], v[12:13]
	s_and_b64 vcc, exec, s[6:7]
	v_pk_mul_f32 v[138:139], v[98:99], v[136:137]
	v_pk_mul_f32 v[104:105], v[86:87], v[136:137]
	v_pk_mul_f32 v[102:103], v[82:83], v[136:137]
	v_pk_mul_f32 v[98:99], v[78:79], v[136:137]
	v_pk_mul_f32 v[86:87], v[140:141], v[136:137]
	v_pk_mul_f32 v[82:83], v[152:153], v[136:137]
	v_pk_mul_f32 v[78:79], v[172:173], v[136:137]
	s_cbranch_vccz .LBB0_578
	v_cvt_pk_bf16_f32 v140, v66, v67
	v_cvt_pk_bf16_f32 v141, v68, v69
	v_mov_b32_e32 v137, v136
	v_mov_b32_e32 v101, v75
	global_store_dwordx2 v[186:187], v[140:141], off offset:-2048
	v_pk_mul_f32 v[140:141], v[100:101], v[136:137]
	v_pk_fma_f32 v[142:143], v[6:7], v[138:139], v[14:15]
	v_pk_fma_f32 v[140:141], v[8:9], v[140:141], v[16:17]
	v_cvt_pk_bf16_f32 v142, v142, v143
	v_cvt_pk_bf16_f32 v143, v140, v141
	v_pk_mul_f32 v[140:141], v[88:89], v[136:137]
	global_store_dwordx2 v[186:187], v[142:143], off offset:-1536
	v_pk_fma_f32 v[140:141], v[20:21], v[140:141], v[28:29]
	v_pk_fma_f32 v[142:143], v[18:19], v[104:105], v[26:27]
	s_mov_b64 s[10:11], 0
	v_cvt_pk_bf16_f32 v142, v142, v143
	v_cvt_pk_bf16_f32 v143, v140, v141
	v_pk_mul_f32 v[140:141], v[84:85], v[136:137]
	global_store_dwordx2 v[186:187], v[142:143], off offset:-1024
	v_pk_fma_f32 v[140:141], v[24:25], v[140:141], v[32:33]
	v_pk_fma_f32 v[142:143], v[22:23], v[102:103], v[30:31]
	s_nop 0
	v_cvt_pk_bf16_f32 v142, v142, v143
	v_cvt_pk_bf16_f32 v143, v140, v141
	v_pk_mul_f32 v[140:141], v[80:81], v[136:137]
	global_store_dwordx2 v[186:187], v[142:143], off offset:-512
	v_pk_fma_f32 v[140:141], v[36:37], v[140:141], v[44:45]
	v_pk_fma_f32 v[142:143], v[34:35], v[98:99], v[42:43]
	s_nop 0
	v_cvt_pk_bf16_f32 v142, v142, v143
	v_cvt_pk_bf16_f32 v143, v140, v141
	v_pk_mul_f32 v[140:141], v[76:77], v[136:137]
	global_store_dwordx2 v[186:187], v[142:143], off
	v_pk_fma_f32 v[140:141], v[40:41], v[140:141], v[48:49]
	v_pk_fma_f32 v[142:143], v[38:39], v[86:87], v[46:47]
	s_nop 0
	v_cvt_pk_bf16_f32 v142, v142, v143
	v_cvt_pk_bf16_f32 v143, v140, v141
	v_pk_mul_f32 v[140:141], v[72:73], v[136:137]
	global_store_dwordx2 v[186:187], v[142:143], off offset:512
	v_pk_fma_f32 v[140:141], v[52:53], v[140:141], v[60:61]
	v_pk_fma_f32 v[142:143], v[50:51], v[82:83], v[58:59]
	s_nop 0
	v_cvt_pk_bf16_f32 v142, v142, v143
	v_cvt_pk_bf16_f32 v143, v140, v141
	v_pk_mul_f32 v[140:141], v[70:71], v[136:137]
	global_store_dwordx2 v[186:187], v[142:143], off offset:1024
	v_pk_fma_f32 v[140:141], v[56:57], v[140:141], v[64:65]
	v_pk_fma_f32 v[142:143], v[54:55], v[78:79], v[62:63]
	s_nop 0
	v_cvt_pk_bf16_f32 v142, v142, v143
	v_cvt_pk_bf16_f32 v143, v140, v141
	global_store_dwordx2 v[186:187], v[142:143], off offset:1536
